# stacked + the two MFMA blocks of each segment interleaved so 4 consecutive accumulator pairs keep the same A-tile operand
# speedup vs baseline: 1.0042x; 1.0042x over previous
.LBB0_120:
	s_add_u32 s28, s40, 0xfff80080
	s_addc_u32 s29, s41, -1
	s_add_i32 s54, 0, 0x10000
	s_cmp_eq_u32 s53, 28
	s_cselect_b32 s29, s23, s29
	s_cselect_b32 s28, s22, s28
	s_cselect_b32 s43, s21, s52
	s_cselect_b32 s42, s50, s51
	s_add_i32 s56, 0, 0x14000
	ds_read_b128 v[130:133], v226
	ds_read_b128 v[134:137], v226 offset:1024
	ds_read_b128 v[138:141], v226 offset:2048
	ds_read_b128 v[142:145], v226 offset:3072
	ds_read_b128 v[146:149], v226 offset:16384
	ds_read_b128 v[150:153], v226 offset:17408
	ds_read_b128 v[154:157], v226 offset:18432
	ds_read_b128 v[158:161], v226 offset:19456
	s_add_i32 m0, s24, 0xc000
	ds_read_b128 v[162:165], v213
	ds_read_b128 v[166:169], v213 offset:1024
	ds_read_b128 v[170:173], v213 offset:2048
	ds_read_b128 v[174:177], v213 offset:3072
	ds_read_b128 v[188:191], v213 offset:4096
	ds_read_b128 v[192:195], v213 offset:5120
	ds_read_b128 v[196:199], v213 offset:6144
	ds_read_b128 v[200:203], v213 offset:7168
	global_load_lds_dwordx4 v184, s[40:41]
	s_add_i32 m0, s24, 0xe000
	s_nop 0
	global_load_lds_dwordx4 v186, s[40:41]
	s_waitcnt vmcnt(8)
	s_waitcnt lgkmcnt(0)
	s_barrier
	v_mfma_f32_16x16x32_bf16 v[126:129], v[130:133], v[162:165], v[126:129]
	v_mfma_f32_16x16x32_bf16 v[126:129], v[134:137], v[166:169], v[126:129]
	v_mfma_f32_16x16x32_bf16 v[122:125], v[142:145], v[166:169], v[122:125]
	v_mfma_f32_16x16x32_bf16 v[122:125], v[138:141], v[162:165], v[122:125]
	v_mfma_f32_16x16x32_bf16 v[118:121], v[146:149], v[162:165], v[118:121]
	v_mfma_f32_16x16x32_bf16 v[118:121], v[150:153], v[166:169], v[118:121]
	v_mfma_f32_16x16x32_bf16 v[114:117], v[158:161], v[166:169], v[114:117]
	v_mfma_f32_16x16x32_bf16 v[114:117], v[154:157], v[162:165], v[114:117]
	v_mfma_f32_16x16x32_bf16 v[98:101], v[154:157], v[170:173], v[98:101]
	v_mfma_f32_16x16x32_bf16 v[98:101], v[158:161], v[174:177], v[98:101]
	v_mfma_f32_16x16x32_bf16 v[106:109], v[142:145], v[174:177], v[106:109]
	v_mfma_f32_16x16x32_bf16 v[106:109], v[138:141], v[170:173], v[106:109]
	v_mfma_f32_16x16x32_bf16 v[110:113], v[130:133], v[170:173], v[110:113]
	v_mfma_f32_16x16x32_bf16 v[110:113], v[134:137], v[174:177], v[110:113]
	v_mfma_f32_16x16x32_bf16 v[102:105], v[150:153], v[174:177], v[102:105]
	v_mfma_f32_16x16x32_bf16 v[102:105], v[146:149], v[170:173], v[102:105]
	v_mfma_f32_16x16x32_bf16 v[86:89], v[146:149], v[188:191], v[86:89]
	v_mfma_f32_16x16x32_bf16 v[86:89], v[150:153], v[192:195], v[86:89]
	v_mfma_f32_16x16x32_bf16 v[94:97], v[134:137], v[192:195], v[94:97]
	v_mfma_f32_16x16x32_bf16 v[94:97], v[130:133], v[188:191], v[94:97]
	v_mfma_f32_16x16x32_bf16 v[90:93], v[138:141], v[188:191], v[90:93]
	v_mfma_f32_16x16x32_bf16 v[90:93], v[142:145], v[192:195], v[90:93]
	v_mfma_f32_16x16x32_bf16 v[82:85], v[158:161], v[192:195], v[82:85]
	v_mfma_f32_16x16x32_bf16 v[82:85], v[154:157], v[188:191], v[82:85]
	v_mfma_f32_16x16x32_bf16 v[66:69], v[154:157], v[196:199], v[66:69]
	v_mfma_f32_16x16x32_bf16 v[66:69], v[158:161], v[200:203], v[66:69]
	v_mfma_f32_16x16x32_bf16 v[74:77], v[142:145], v[200:203], v[74:77]
	v_mfma_f32_16x16x32_bf16 v[74:77], v[138:141], v[196:199], v[74:77]
	v_mfma_f32_16x16x32_bf16 v[78:81], v[130:133], v[196:199], v[78:81]
	v_mfma_f32_16x16x32_bf16 v[78:81], v[134:137], v[200:203], v[78:81]
	v_mfma_f32_16x16x32_bf16 v[70:73], v[150:153], v[200:203], v[70:73]
	v_mfma_f32_16x16x32_bf16 v[70:73], v[146:149], v[196:199], v[70:73]
	s_barrier
	s_add_i32 s54, s54, s1
	v_lshl_add_u64 v[204:205], s[42:43], 0, v[32:33]
	s_mov_b32 m0, s54
	ds_read_b128 v[162:165], v213 offset:16384
	ds_read_b128 v[166:169], v213 offset:17408
	ds_read_b128 v[170:173], v213 offset:18432
	ds_read_b128 v[174:177], v213 offset:19456
	ds_read_b128 v[188:191], v213 offset:20480
	ds_read_b128 v[192:195], v213 offset:21504
	ds_read_b128 v[196:199], v213 offset:22528
	ds_read_b128 v[200:203], v213 offset:23552
	global_load_lds_dwordx4 v[204:205], off
	s_add_i32 m0, s54, 0x2000
	s_add_u32 s54, s42, 0x80000
	v_lshl_add_u64 v[206:207], s[42:43], 0, v[182:183]
	s_addc_u32 s55, s43, 0
	s_add_i32 s56, s56, s1
	global_load_lds_dwordx4 v[206:207], off
	s_mov_b32 m0, s56
	v_lshl_add_u64 v[214:215], s[28:29], 0, v[180:181]
	global_load_lds_dwordx4 v32, s[54:55]
	s_add_i32 m0, s56, 0x2000
	s_nop 0
	global_load_lds_dwordx4 v182, s[54:55]
	v_lshl_add_u64 v[208:209], s[28:29], 0, v[178:179]
	s_mov_b32 m0, s24
	s_nop 0
	global_load_lds_dwordx4 v[208:209], off
	s_mov_b32 m0, s25
	s_nop 0
	global_load_lds_dwordx4 v[214:215], off
	s_waitcnt vmcnt(8)
	s_waitcnt lgkmcnt(0)
	s_barrier
	v_mfma_f32_16x16x32_bf16 v[62:65], v[130:133], v[162:165], v[62:65]
	v_mfma_f32_16x16x32_bf16 v[62:65], v[134:137], v[166:169], v[62:65]
	v_mfma_f32_16x16x32_bf16 v[58:61], v[142:145], v[166:169], v[58:61]
	v_mfma_f32_16x16x32_bf16 v[58:61], v[138:141], v[162:165], v[58:61]
	v_mfma_f32_16x16x32_bf16 v[54:57], v[146:149], v[162:165], v[54:57]
	v_mfma_f32_16x16x32_bf16 v[54:57], v[150:153], v[166:169], v[54:57]
	v_mfma_f32_16x16x32_bf16 v[50:53], v[158:161], v[166:169], v[50:53]
	v_mfma_f32_16x16x32_bf16 v[50:53], v[154:157], v[162:165], v[50:53]
	v_mfma_f32_16x16x32_bf16 v[34:37], v[154:157], v[170:173], v[34:37]
	v_mfma_f32_16x16x32_bf16 v[34:37], v[158:161], v[174:177], v[34:37]
	v_mfma_f32_16x16x32_bf16 v[42:45], v[142:145], v[174:177], v[42:45]
	v_mfma_f32_16x16x32_bf16 v[42:45], v[138:141], v[170:173], v[42:45]
	v_mfma_f32_16x16x32_bf16 v[46:49], v[130:133], v[170:173], v[46:49]
	v_mfma_f32_16x16x32_bf16 v[46:49], v[134:137], v[174:177], v[46:49]
	v_mfma_f32_16x16x32_bf16 v[38:41], v[150:153], v[174:177], v[38:41]
	v_mfma_f32_16x16x32_bf16 v[38:41], v[146:149], v[170:173], v[38:41]
	v_mfma_f32_16x16x32_bf16 v[20:23], v[146:149], v[188:191], v[20:23]
	v_mfma_f32_16x16x32_bf16 v[20:23], v[150:153], v[192:195], v[20:23]
	v_mfma_f32_16x16x32_bf16 v[28:31], v[134:137], v[192:195], v[28:31]
	v_mfma_f32_16x16x32_bf16 v[28:31], v[130:133], v[188:191], v[28:31]
	v_mfma_f32_16x16x32_bf16 v[24:27], v[138:141], v[188:191], v[24:27]
	v_mfma_f32_16x16x32_bf16 v[24:27], v[142:145], v[192:195], v[24:27]
	v_mfma_f32_16x16x32_bf16 v[16:19], v[158:161], v[192:195], v[16:19]
	v_mfma_f32_16x16x32_bf16 v[16:19], v[154:157], v[188:191], v[16:19]
	v_mfma_f32_16x16x32_bf16 v[0:3], v[154:157], v[196:199], v[0:3]
	v_mfma_f32_16x16x32_bf16 v[0:3], v[158:161], v[200:203], v[0:3]
	v_mfma_f32_16x16x32_bf16 v[8:11], v[142:145], v[200:203], v[8:11]
	v_mfma_f32_16x16x32_bf16 v[8:11], v[138:141], v[196:199], v[8:11]
	v_mfma_f32_16x16x32_bf16 v[12:15], v[130:133], v[196:199], v[12:15]
	v_mfma_f32_16x16x32_bf16 v[12:15], v[134:137], v[200:203], v[12:15]
	v_mfma_f32_16x16x32_bf16 v[4:7], v[150:153], v[200:203], v[4:7]
	v_mfma_f32_16x16x32_bf16 v[4:7], v[146:149], v[196:199], v[4:7]
	s_barrier
	s_add_i32 s54, 0, 0x18000
	s_add_i32 s55, 0, 0x1c000
	ds_read_b128 v[130:133], v226 offset:32768
	ds_read_b128 v[134:137], v226 offset:33792
	ds_read_b128 v[138:141], v226 offset:34816
	ds_read_b128 v[142:145], v226 offset:35840
	ds_read_b128 v[146:149], v226 offset:49152
	ds_read_b128 v[150:153], v226 offset:50176
	ds_read_b128 v[154:157], v226 offset:51200
	ds_read_b128 v[158:161], v226 offset:52224
	s_add_u32 s28, s28, 0x80000
	s_addc_u32 s29, s29, 0
	s_mov_b32 m0, s33
	ds_read_b128 v[162:165], v213 offset:32768
	ds_read_b128 v[166:169], v213 offset:33792
	ds_read_b128 v[170:173], v213 offset:34816
	ds_read_b128 v[174:177], v213 offset:35840
	ds_read_b128 v[188:191], v213 offset:36864
	ds_read_b128 v[192:195], v213 offset:37888
	ds_read_b128 v[196:199], v213 offset:38912
	ds_read_b128 v[200:203], v213 offset:39936
	global_load_lds_dwordx4 v178, s[28:29]
	s_mov_b32 m0, s36
	s_nop 0
	global_load_lds_dwordx4 v180, s[28:29]
	s_waitcnt vmcnt(8)
	s_waitcnt lgkmcnt(0)
	s_barrier
	v_mfma_f32_16x16x32_bf16 v[126:129], v[130:133], v[162:165], v[126:129]
	v_mfma_f32_16x16x32_bf16 v[126:129], v[134:137], v[166:169], v[126:129]
	v_mfma_f32_16x16x32_bf16 v[122:125], v[142:145], v[166:169], v[122:125]
	v_mfma_f32_16x16x32_bf16 v[122:125], v[138:141], v[162:165], v[122:125]
	v_mfma_f32_16x16x32_bf16 v[118:121], v[146:149], v[162:165], v[118:121]
	v_mfma_f32_16x16x32_bf16 v[118:121], v[150:153], v[166:169], v[118:121]
	v_mfma_f32_16x16x32_bf16 v[114:117], v[158:161], v[166:169], v[114:117]
	v_mfma_f32_16x16x32_bf16 v[114:117], v[154:157], v[162:165], v[114:117]
	v_mfma_f32_16x16x32_bf16 v[98:101], v[154:157], v[170:173], v[98:101]
	v_mfma_f32_16x16x32_bf16 v[98:101], v[158:161], v[174:177], v[98:101]
	v_mfma_f32_16x16x32_bf16 v[106:109], v[142:145], v[174:177], v[106:109]
	v_mfma_f32_16x16x32_bf16 v[106:109], v[138:141], v[170:173], v[106:109]
	v_mfma_f32_16x16x32_bf16 v[110:113], v[130:133], v[170:173], v[110:113]
	v_mfma_f32_16x16x32_bf16 v[110:113], v[134:137], v[174:177], v[110:113]
	v_mfma_f32_16x16x32_bf16 v[102:105], v[150:153], v[174:177], v[102:105]
	v_mfma_f32_16x16x32_bf16 v[102:105], v[146:149], v[170:173], v[102:105]
	v_mfma_f32_16x16x32_bf16 v[86:89], v[146:149], v[188:191], v[86:89]
	v_mfma_f32_16x16x32_bf16 v[86:89], v[150:153], v[192:195], v[86:89]
	v_mfma_f32_16x16x32_bf16 v[94:97], v[134:137], v[192:195], v[94:97]
	v_mfma_f32_16x16x32_bf16 v[94:97], v[130:133], v[188:191], v[94:97]
	v_mfma_f32_16x16x32_bf16 v[90:93], v[138:141], v[188:191], v[90:93]
	v_mfma_f32_16x16x32_bf16 v[90:93], v[142:145], v[192:195], v[90:93]
	v_mfma_f32_16x16x32_bf16 v[82:85], v[158:161], v[192:195], v[82:85]
	v_mfma_f32_16x16x32_bf16 v[82:85], v[154:157], v[188:191], v[82:85]
	v_mfma_f32_16x16x32_bf16 v[66:69], v[154:157], v[196:199], v[66:69]
	v_mfma_f32_16x16x32_bf16 v[66:69], v[158:161], v[200:203], v[66:69]
	v_mfma_f32_16x16x32_bf16 v[74:77], v[142:145], v[200:203], v[74:77]
	v_mfma_f32_16x16x32_bf16 v[74:77], v[138:141], v[196:199], v[74:77]
	v_mfma_f32_16x16x32_bf16 v[78:81], v[130:133], v[196:199], v[78:81]
	v_mfma_f32_16x16x32_bf16 v[78:81], v[134:137], v[200:203], v[78:81]
	v_mfma_f32_16x16x32_bf16 v[70:73], v[150:153], v[200:203], v[70:73]
	v_mfma_f32_16x16x32_bf16 v[70:73], v[146:149], v[196:199], v[70:73]
	s_barrier
	s_add_i32 s28, s54, s1
	v_lshl_add_u64 v[204:205], v[204:205], 0, s[34:35]
	s_mov_b32 m0, s28
	ds_read_b128 v[162:165], v213 offset:49152
	ds_read_b128 v[166:169], v213 offset:50176
	ds_read_b128 v[170:173], v213 offset:51200
	ds_read_b128 v[174:177], v213 offset:52224
	ds_read_b128 v[188:191], v213 offset:53248
	ds_read_b128 v[192:195], v213 offset:54272
	ds_read_b128 v[196:199], v213 offset:55296
	ds_read_b128 v[200:203], v213 offset:56320
	global_load_lds_dwordx4 v[204:205], off
	s_add_i32 m0, s28, 0x2000
	s_add_u32 s28, s42, 0x80080
	v_lshl_add_u64 v[204:205], v[206:207], 0, s[34:35]
	s_addc_u32 s29, s43, 0
	s_add_i32 s42, s55, s1
	global_load_lds_dwordx4 v[204:205], off
	s_mov_b32 m0, s42
	s_nop 0
	global_load_lds_dwordx4 v32, s[28:29]
	s_add_i32 m0, s42, 0x2000
	s_nop 0
	global_load_lds_dwordx4 v182, s[28:29]
	v_lshl_add_u64 v[204:205], v[208:209], 0, s[34:35]
	s_mov_b32 m0, s44
	s_nop 0
	global_load_lds_dwordx4 v[204:205], off
	v_lshl_add_u64 v[204:205], v[214:215], 0, s[34:35]
	s_mov_b32 m0, s45
	s_nop 0
	global_load_lds_dwordx4 v[204:205], off
	s_waitcnt vmcnt(8)
	s_waitcnt lgkmcnt(0)
	s_barrier
	v_mfma_f32_16x16x32_bf16 v[62:65], v[130:133], v[162:165], v[62:65]
	v_mfma_f32_16x16x32_bf16 v[62:65], v[134:137], v[166:169], v[62:65]
	v_mfma_f32_16x16x32_bf16 v[58:61], v[142:145], v[166:169], v[58:61]
	v_mfma_f32_16x16x32_bf16 v[58:61], v[138:141], v[162:165], v[58:61]
	v_mfma_f32_16x16x32_bf16 v[54:57], v[146:149], v[162:165], v[54:57]
	v_mfma_f32_16x16x32_bf16 v[54:57], v[150:153], v[166:169], v[54:57]
	v_mfma_f32_16x16x32_bf16 v[50:53], v[158:161], v[166:169], v[50:53]
	v_mfma_f32_16x16x32_bf16 v[50:53], v[154:157], v[162:165], v[50:53]
	v_mfma_f32_16x16x32_bf16 v[34:37], v[154:157], v[170:173], v[34:37]
	v_mfma_f32_16x16x32_bf16 v[34:37], v[158:161], v[174:177], v[34:37]
	v_mfma_f32_16x16x32_bf16 v[42:45], v[142:145], v[174:177], v[42:45]
	v_mfma_f32_16x16x32_bf16 v[42:45], v[138:141], v[170:173], v[42:45]
	v_mfma_f32_16x16x32_bf16 v[46:49], v[130:133], v[170:173], v[46:49]
	v_mfma_f32_16x16x32_bf16 v[46:49], v[134:137], v[174:177], v[46:49]
	v_mfma_f32_16x16x32_bf16 v[38:41], v[150:153], v[174:177], v[38:41]
	v_mfma_f32_16x16x32_bf16 v[38:41], v[146:149], v[170:173], v[38:41]
	v_mfma_f32_16x16x32_bf16 v[20:23], v[146:149], v[188:191], v[20:23]
	v_mfma_f32_16x16x32_bf16 v[20:23], v[150:153], v[192:195], v[20:23]
	v_mfma_f32_16x16x32_bf16 v[28:31], v[134:137], v[192:195], v[28:31]
	v_mfma_f32_16x16x32_bf16 v[28:31], v[130:133], v[188:191], v[28:31]
	v_mfma_f32_16x16x32_bf16 v[24:27], v[138:141], v[188:191], v[24:27]
	v_mfma_f32_16x16x32_bf16 v[24:27], v[142:145], v[192:195], v[24:27]
	v_mfma_f32_16x16x32_bf16 v[16:19], v[158:161], v[192:195], v[16:19]
	v_mfma_f32_16x16x32_bf16 v[16:19], v[154:157], v[188:191], v[16:19]
	v_mfma_f32_16x16x32_bf16 v[0:3], v[154:157], v[196:199], v[0:3]
	v_mfma_f32_16x16x32_bf16 v[0:3], v[158:161], v[200:203], v[0:3]
	v_mfma_f32_16x16x32_bf16 v[8:11], v[142:145], v[200:203], v[8:11]
	v_mfma_f32_16x16x32_bf16 v[8:11], v[138:141], v[196:199], v[8:11]
	v_mfma_f32_16x16x32_bf16 v[12:15], v[130:133], v[196:199], v[12:15]
	v_mfma_f32_16x16x32_bf16 v[12:15], v[134:137], v[200:203], v[12:15]
	v_mfma_f32_16x16x32_bf16 v[4:7], v[150:153], v[200:203], v[4:7]
	v_mfma_f32_16x16x32_bf16 v[4:7], v[146:149], v[196:199], v[4:7]
	s_barrier
	s_add_i32 s53, s53, 2
	s_add_u32 s40, s40, 0x100
	s_addc_u32 s41, s41, 0
	s_add_u32 s51, s51, 0x100
	s_addc_u32 s52, s52, 0
	s_cmp_gt_u32 s53, 29
	s_cbranch_scc0 .LBB0_120
	s_setprio 0
	s_and_b64 vcc, exec, s[18:19]
	s_cbranch_vccz .LBB0_123
	s_barrier

.LBB0_685:
	s_add_u32 s28, s16, s40
	s_addc_u32 s29, s17, s41
	s_add_u32 s28, s28, 0x100
	s_addc_u32 s29, s29, 0
	s_add_u32 s42, s52, s40
	s_addc_u32 s43, s53, s41
	s_add_i32 s56, 0, 0x10000
	s_cmpk_eq_i32 s40, 0xf00
	s_cselect_b32 s29, s39, s29
	s_cselect_b32 s28, s38, s28
	s_cselect_b32 s43, s23, s43
	s_cselect_b32 s42, s54, s42
	s_add_i32 s58, 0, 0x14000
	ds_read_b128 v[134:137], v224
	ds_read_b128 v[138:141], v224 offset:1024
	ds_read_b128 v[142:145], v224 offset:2048
	ds_read_b128 v[146:149], v224 offset:3072
	ds_read_b128 v[150:153], v224 offset:16384
	ds_read_b128 v[154:157], v224 offset:17408
	ds_read_b128 v[158:161], v224 offset:18432
	ds_read_b128 v[162:165], v224 offset:19456
	v_lshl_add_u64 v[212:213], v[130:131], 0, s[40:41]
	s_add_i32 m0, s24, 0xc000
	ds_read_b128 v[166:169], v191
	ds_read_b128 v[180:183], v191 offset:1024
	ds_read_b128 v[184:187], v191 offset:2048
	ds_read_b128 v[192:195], v191 offset:3072
	ds_read_b128 v[196:199], v191 offset:4096
	ds_read_b128 v[200:203], v191 offset:5120
	ds_read_b128 v[204:207], v191 offset:6144
	ds_read_b128 v[208:211], v191 offset:7168
	global_load_lds_dwordx4 v[212:213], off
	v_lshl_add_u64 v[212:213], v[132:133], 0, s[40:41]
	s_add_i32 m0, s24, 0xe000
	s_nop 0
	global_load_lds_dwordx4 v[212:213], off
	s_waitcnt vmcnt(8)
	s_waitcnt lgkmcnt(0)
	s_barrier
	v_mfma_f32_16x16x32_bf16 v[82:85], v[134:137], v[166:169], v[82:85]
	v_mfma_f32_16x16x32_bf16 v[82:85], v[138:141], v[180:183], v[82:85]
	v_mfma_f32_16x16x32_bf16 v[78:81], v[146:149], v[180:183], v[78:81]
	v_mfma_f32_16x16x32_bf16 v[78:81], v[142:145], v[166:169], v[78:81]
	v_mfma_f32_16x16x32_bf16 v[50:53], v[150:153], v[166:169], v[50:53]
	v_mfma_f32_16x16x32_bf16 v[50:53], v[154:157], v[180:183], v[50:53]
	v_mfma_f32_16x16x32_bf16 v[46:49], v[162:165], v[180:183], v[46:49]
	v_mfma_f32_16x16x32_bf16 v[46:49], v[158:161], v[166:169], v[46:49]
	v_mfma_f32_16x16x32_bf16 v[38:41], v[158:161], v[184:187], v[38:41]
	v_mfma_f32_16x16x32_bf16 v[38:41], v[162:165], v[192:195], v[38:41]
	v_mfma_f32_16x16x32_bf16 v[70:73], v[146:149], v[192:195], v[70:73]
	v_mfma_f32_16x16x32_bf16 v[70:73], v[142:145], v[184:187], v[70:73]
	v_mfma_f32_16x16x32_bf16 v[74:77], v[134:137], v[184:187], v[74:77]
	v_mfma_f32_16x16x32_bf16 v[74:77], v[138:141], v[192:195], v[74:77]
	v_mfma_f32_16x16x32_bf16 v[42:45], v[154:157], v[192:195], v[42:45]
	v_mfma_f32_16x16x32_bf16 v[42:45], v[150:153], v[184:187], v[42:45]
	v_mfma_f32_16x16x32_bf16 v[34:37], v[150:153], v[196:199], v[34:37]
	v_mfma_f32_16x16x32_bf16 v[34:37], v[154:157], v[200:203], v[34:37]
	v_mfma_f32_16x16x32_bf16 v[66:69], v[138:141], v[200:203], v[66:69]
	v_mfma_f32_16x16x32_bf16 v[66:69], v[134:137], v[196:199], v[66:69]
	v_mfma_f32_16x16x32_bf16 v[62:65], v[142:145], v[196:199], v[62:65]
	v_mfma_f32_16x16x32_bf16 v[62:65], v[146:149], v[200:203], v[62:65]
	v_mfma_f32_16x16x32_bf16 v[28:31], v[162:165], v[200:203], v[28:31]
	v_mfma_f32_16x16x32_bf16 v[28:31], v[158:161], v[196:199], v[28:31]
	v_mfma_f32_16x16x32_bf16 v[20:23], v[158:161], v[204:207], v[20:23]
	v_mfma_f32_16x16x32_bf16 v[20:23], v[162:165], v[208:211], v[20:23]
	v_mfma_f32_16x16x32_bf16 v[54:57], v[146:149], v[208:211], v[54:57]
	v_mfma_f32_16x16x32_bf16 v[54:57], v[142:145], v[204:207], v[54:57]
	v_mfma_f32_16x16x32_bf16 v[58:61], v[134:137], v[204:207], v[58:61]
	v_mfma_f32_16x16x32_bf16 v[58:61], v[138:141], v[208:211], v[58:61]
	v_mfma_f32_16x16x32_bf16 v[24:27], v[154:157], v[208:211], v[24:27]
	v_mfma_f32_16x16x32_bf16 v[24:27], v[150:153], v[204:207], v[24:27]
	s_barrier
	s_add_i32 s56, s56, s13
	v_lshl_add_u64 v[212:213], s[42:43], 0, v[32:33]
	s_mov_b32 m0, s56
	ds_read_b128 v[166:169], v191 offset:16384
	ds_read_b128 v[180:183], v191 offset:17408
	ds_read_b128 v[184:187], v191 offset:18432
	ds_read_b128 v[192:195], v191 offset:19456
	ds_read_b128 v[196:199], v191 offset:20480
	ds_read_b128 v[200:203], v191 offset:21504
	ds_read_b128 v[204:207], v191 offset:22528
	ds_read_b128 v[208:211], v191 offset:23552
	global_load_lds_dwordx4 v[212:213], off
	s_add_i32 m0, s56, 0x2000
	s_add_u32 s56, s42, 0x80000
	v_lshl_add_u64 v[214:215], s[42:43], 0, v[174:175]
	s_addc_u32 s57, s43, 0
	s_add_i32 s58, s58, s13
	global_load_lds_dwordx4 v[214:215], off
	s_mov_b32 m0, s58
	v_lshl_add_u64 v[220:221], s[28:29], 0, v[172:173]
	global_load_lds_dwordx4 v32, s[56:57]
	s_add_i32 m0, s58, 0x2000
	s_nop 0
	global_load_lds_dwordx4 v174, s[56:57]
	v_lshl_add_u64 v[216:217], s[28:29], 0, v[170:171]
	s_mov_b32 m0, s24
	s_nop 0
	global_load_lds_dwordx4 v[216:217], off
	s_mov_b32 m0, s25
	s_nop 0
	global_load_lds_dwordx4 v[220:221], off
	s_waitcnt vmcnt(8)
	s_waitcnt lgkmcnt(0)
	s_barrier
	v_mfma_f32_16x16x32_bf16 v[16:19], v[134:137], v[166:169], v[16:19]
	v_mfma_f32_16x16x32_bf16 v[16:19], v[138:141], v[180:183], v[16:19]
	v_mfma_f32_16x16x32_bf16 v[12:15], v[146:149], v[180:183], v[12:15]
	v_mfma_f32_16x16x32_bf16 v[12:15], v[142:145], v[166:169], v[12:15]
	v_mfma_f32_16x16x32_bf16 v[98:101], v[150:153], v[166:169], v[98:101]
	v_mfma_f32_16x16x32_bf16 v[98:101], v[154:157], v[180:183], v[98:101]
	v_mfma_f32_16x16x32_bf16 v[102:105], v[162:165], v[180:183], v[102:105]
	v_mfma_f32_16x16x32_bf16 v[102:105], v[158:161], v[166:169], v[102:105]
	v_mfma_f32_16x16x32_bf16 v[110:113], v[158:161], v[184:187], v[110:113]
	v_mfma_f32_16x16x32_bf16 v[110:113], v[162:165], v[192:195], v[110:113]
	v_mfma_f32_16x16x32_bf16 v[4:7], v[146:149], v[192:195], v[4:7]
	v_mfma_f32_16x16x32_bf16 v[4:7], v[142:145], v[184:187], v[4:7]
	v_mfma_f32_16x16x32_bf16 v[8:11], v[134:137], v[184:187], v[8:11]
	v_mfma_f32_16x16x32_bf16 v[8:11], v[138:141], v[192:195], v[8:11]
	v_mfma_f32_16x16x32_bf16 v[106:109], v[154:157], v[192:195], v[106:109]
	v_mfma_f32_16x16x32_bf16 v[106:109], v[150:153], v[184:187], v[106:109]
	v_mfma_f32_16x16x32_bf16 v[114:117], v[150:153], v[196:199], v[114:117]
	v_mfma_f32_16x16x32_bf16 v[114:117], v[154:157], v[200:203], v[114:117]
	v_mfma_f32_16x16x32_bf16 v[0:3], v[138:141], v[200:203], v[0:3]
	v_mfma_f32_16x16x32_bf16 v[0:3], v[134:137], v[196:199], v[0:3]
	v_mfma_f32_16x16x32_bf16 v[86:89], v[142:145], v[196:199], v[86:89]
	v_mfma_f32_16x16x32_bf16 v[86:89], v[146:149], v[200:203], v[86:89]
	v_mfma_f32_16x16x32_bf16 v[118:121], v[162:165], v[200:203], v[118:121]
	v_mfma_f32_16x16x32_bf16 v[118:121], v[158:161], v[196:199], v[118:121]
	v_mfma_f32_16x16x32_bf16 v[126:129], v[158:161], v[204:207], v[126:129]
	v_mfma_f32_16x16x32_bf16 v[126:129], v[162:165], v[208:211], v[126:129]
	v_mfma_f32_16x16x32_bf16 v[94:97], v[146:149], v[208:211], v[94:97]
	v_mfma_f32_16x16x32_bf16 v[94:97], v[142:145], v[204:207], v[94:97]
	v_mfma_f32_16x16x32_bf16 v[90:93], v[134:137], v[204:207], v[90:93]
	v_mfma_f32_16x16x32_bf16 v[90:93], v[138:141], v[208:211], v[90:93]
	v_mfma_f32_16x16x32_bf16 v[122:125], v[154:157], v[208:211], v[122:125]
	v_mfma_f32_16x16x32_bf16 v[122:125], v[150:153], v[204:207], v[122:125]
	s_barrier
	s_add_i32 s56, 0, 0x18000
	s_add_i32 s57, 0, 0x1c000
	ds_read_b128 v[134:137], v224 offset:32768
	ds_read_b128 v[138:141], v224 offset:33792
	ds_read_b128 v[142:145], v224 offset:34816
	ds_read_b128 v[146:149], v224 offset:35840
	ds_read_b128 v[150:153], v224 offset:49152
	ds_read_b128 v[154:157], v224 offset:50176
	ds_read_b128 v[158:161], v224 offset:51200
	ds_read_b128 v[162:165], v224 offset:52224
	s_add_u32 s28, s28, 0x80000
	s_addc_u32 s29, s29, 0
	s_mov_b32 m0, s33
	ds_read_b128 v[166:169], v191 offset:32768
	ds_read_b128 v[180:183], v191 offset:33792
	ds_read_b128 v[184:187], v191 offset:34816
	ds_read_b128 v[192:195], v191 offset:35840
	ds_read_b128 v[196:199], v191 offset:36864
	ds_read_b128 v[200:203], v191 offset:37888
	ds_read_b128 v[204:207], v191 offset:38912
	ds_read_b128 v[208:211], v191 offset:39936
	global_load_lds_dwordx4 v170, s[28:29]
	s_mov_b32 m0, s36
	s_nop 0
	global_load_lds_dwordx4 v172, s[28:29]
	s_waitcnt vmcnt(8)
	s_waitcnt lgkmcnt(0)
	s_barrier
	v_mfma_f32_16x16x32_bf16 v[82:85], v[134:137], v[166:169], v[82:85]
	v_mfma_f32_16x16x32_bf16 v[82:85], v[138:141], v[180:183], v[82:85]
	v_mfma_f32_16x16x32_bf16 v[78:81], v[146:149], v[180:183], v[78:81]
	v_mfma_f32_16x16x32_bf16 v[78:81], v[142:145], v[166:169], v[78:81]
	v_mfma_f32_16x16x32_bf16 v[50:53], v[150:153], v[166:169], v[50:53]
	v_mfma_f32_16x16x32_bf16 v[50:53], v[154:157], v[180:183], v[50:53]
	v_mfma_f32_16x16x32_bf16 v[46:49], v[162:165], v[180:183], v[46:49]
	v_mfma_f32_16x16x32_bf16 v[46:49], v[158:161], v[166:169], v[46:49]
	v_mfma_f32_16x16x32_bf16 v[38:41], v[158:161], v[184:187], v[38:41]
	v_mfma_f32_16x16x32_bf16 v[38:41], v[162:165], v[192:195], v[38:41]
	v_mfma_f32_16x16x32_bf16 v[70:73], v[146:149], v[192:195], v[70:73]
	v_mfma_f32_16x16x32_bf16 v[70:73], v[142:145], v[184:187], v[70:73]
	v_mfma_f32_16x16x32_bf16 v[74:77], v[134:137], v[184:187], v[74:77]
	v_mfma_f32_16x16x32_bf16 v[74:77], v[138:141], v[192:195], v[74:77]
	v_mfma_f32_16x16x32_bf16 v[42:45], v[154:157], v[192:195], v[42:45]
	v_mfma_f32_16x16x32_bf16 v[42:45], v[150:153], v[184:187], v[42:45]
	v_mfma_f32_16x16x32_bf16 v[34:37], v[150:153], v[196:199], v[34:37]
	v_mfma_f32_16x16x32_bf16 v[34:37], v[154:157], v[200:203], v[34:37]
	v_mfma_f32_16x16x32_bf16 v[66:69], v[138:141], v[200:203], v[66:69]
	v_mfma_f32_16x16x32_bf16 v[66:69], v[134:137], v[196:199], v[66:69]
	v_mfma_f32_16x16x32_bf16 v[62:65], v[142:145], v[196:199], v[62:65]
	v_mfma_f32_16x16x32_bf16 v[62:65], v[146:149], v[200:203], v[62:65]
	v_mfma_f32_16x16x32_bf16 v[28:31], v[162:165], v[200:203], v[28:31]
	v_mfma_f32_16x16x32_bf16 v[28:31], v[158:161], v[196:199], v[28:31]
	v_mfma_f32_16x16x32_bf16 v[20:23], v[158:161], v[204:207], v[20:23]
	v_mfma_f32_16x16x32_bf16 v[20:23], v[162:165], v[208:211], v[20:23]
	v_mfma_f32_16x16x32_bf16 v[54:57], v[146:149], v[208:211], v[54:57]
	v_mfma_f32_16x16x32_bf16 v[54:57], v[142:145], v[204:207], v[54:57]
	v_mfma_f32_16x16x32_bf16 v[58:61], v[134:137], v[204:207], v[58:61]
	v_mfma_f32_16x16x32_bf16 v[58:61], v[138:141], v[208:211], v[58:61]
	v_mfma_f32_16x16x32_bf16 v[24:27], v[154:157], v[208:211], v[24:27]
	v_mfma_f32_16x16x32_bf16 v[24:27], v[150:153], v[204:207], v[24:27]
	s_barrier
	s_add_i32 s28, s56, s13
	v_lshl_add_u64 v[212:213], v[212:213], 0, s[34:35]
	s_mov_b32 m0, s28
	ds_read_b128 v[166:169], v191 offset:49152
	ds_read_b128 v[180:183], v191 offset:50176
	ds_read_b128 v[184:187], v191 offset:51200
	ds_read_b128 v[192:195], v191 offset:52224
	ds_read_b128 v[196:199], v191 offset:53248
	ds_read_b128 v[200:203], v191 offset:54272
	ds_read_b128 v[204:207], v191 offset:55296
	ds_read_b128 v[208:211], v191 offset:56320
	global_load_lds_dwordx4 v[212:213], off
	s_add_i32 m0, s28, 0x2000
	s_add_u32 s28, s42, 0x80080
	v_lshl_add_u64 v[212:213], v[214:215], 0, s[34:35]
	s_addc_u32 s29, s43, 0
	s_add_i32 s42, s57, s13
	global_load_lds_dwordx4 v[212:213], off
	s_mov_b32 m0, s42
	s_nop 0
	global_load_lds_dwordx4 v32, s[28:29]
	s_add_i32 m0, s42, 0x2000
	s_nop 0
	global_load_lds_dwordx4 v174, s[28:29]
	v_lshl_add_u64 v[212:213], v[216:217], 0, s[34:35]
	s_mov_b32 m0, s45
	s_nop 0
	global_load_lds_dwordx4 v[212:213], off
	v_lshl_add_u64 v[212:213], v[220:221], 0, s[34:35]
	s_mov_b32 m0, s46
	s_nop 0
	global_load_lds_dwordx4 v[212:213], off
	s_waitcnt vmcnt(8)
	s_waitcnt lgkmcnt(0)
	s_barrier
	v_mfma_f32_16x16x32_bf16 v[16:19], v[134:137], v[166:169], v[16:19]
	v_mfma_f32_16x16x32_bf16 v[16:19], v[138:141], v[180:183], v[16:19]
	v_mfma_f32_16x16x32_bf16 v[12:15], v[146:149], v[180:183], v[12:15]
	v_mfma_f32_16x16x32_bf16 v[12:15], v[142:145], v[166:169], v[12:15]
	v_mfma_f32_16x16x32_bf16 v[98:101], v[150:153], v[166:169], v[98:101]
	v_mfma_f32_16x16x32_bf16 v[98:101], v[154:157], v[180:183], v[98:101]
	v_mfma_f32_16x16x32_bf16 v[102:105], v[162:165], v[180:183], v[102:105]
	v_mfma_f32_16x16x32_bf16 v[102:105], v[158:161], v[166:169], v[102:105]
	v_mfma_f32_16x16x32_bf16 v[110:113], v[158:161], v[184:187], v[110:113]
	v_mfma_f32_16x16x32_bf16 v[110:113], v[162:165], v[192:195], v[110:113]
	v_mfma_f32_16x16x32_bf16 v[4:7], v[146:149], v[192:195], v[4:7]
	v_mfma_f32_16x16x32_bf16 v[4:7], v[142:145], v[184:187], v[4:7]
	v_mfma_f32_16x16x32_bf16 v[8:11], v[134:137], v[184:187], v[8:11]
	v_mfma_f32_16x16x32_bf16 v[8:11], v[138:141], v[192:195], v[8:11]
	v_mfma_f32_16x16x32_bf16 v[106:109], v[154:157], v[192:195], v[106:109]
	v_mfma_f32_16x16x32_bf16 v[106:109], v[150:153], v[184:187], v[106:109]
	v_mfma_f32_16x16x32_bf16 v[114:117], v[150:153], v[196:199], v[114:117]
	v_mfma_f32_16x16x32_bf16 v[114:117], v[154:157], v[200:203], v[114:117]
	v_mfma_f32_16x16x32_bf16 v[0:3], v[138:141], v[200:203], v[0:3]
	v_mfma_f32_16x16x32_bf16 v[0:3], v[134:137], v[196:199], v[0:3]
	v_mfma_f32_16x16x32_bf16 v[86:89], v[142:145], v[196:199], v[86:89]
	v_mfma_f32_16x16x32_bf16 v[86:89], v[146:149], v[200:203], v[86:89]
	v_mfma_f32_16x16x32_bf16 v[118:121], v[162:165], v[200:203], v[118:121]
	v_mfma_f32_16x16x32_bf16 v[118:121], v[158:161], v[196:199], v[118:121]
	v_mfma_f32_16x16x32_bf16 v[126:129], v[158:161], v[204:207], v[126:129]
	v_mfma_f32_16x16x32_bf16 v[126:129], v[162:165], v[208:211], v[126:129]
	v_mfma_f32_16x16x32_bf16 v[94:97], v[146:149], v[208:211], v[94:97]
	v_mfma_f32_16x16x32_bf16 v[94:97], v[142:145], v[204:207], v[94:97]
	v_mfma_f32_16x16x32_bf16 v[90:93], v[134:137], v[204:207], v[90:93]
	v_mfma_f32_16x16x32_bf16 v[90:93], v[138:141], v[208:211], v[90:93]
	v_mfma_f32_16x16x32_bf16 v[122:125], v[154:157], v[208:211], v[122:125]
	v_mfma_f32_16x16x32_bf16 v[122:125], v[150:153], v[204:207], v[122:125]
	s_barrier
	s_add_i32 s55, s55, 2
	s_add_u32 s40, s40, 0x100
	s_addc_u32 s41, s41, 0
	s_cmp_gt_u32 s55, 29
	s_cbranch_scc0 .LBB0_685
	s_setprio 0
	s_and_b64 vcc, exec, s[18:19]
	s_cbranch_vccz .LBB0_688
	s_barrier

.LBB0_755:
	s_add_u32 s6, s4, 0x100
	s_addc_u32 s7, s5, 0
	s_add_i32 s52, 0, 0x10000
	s_cmpk_eq_i32 s51, 0x54
	s_cselect_b32 s29, s23, s7
	s_cselect_b32 s28, s22, s6
	s_cselect_b32 s31, s27, s50
	s_cselect_b32 s30, s26, s33
	s_add_i32 s53, 0, 0x14000
	ds_read_b128 v[130:133], v248
	ds_read_b128 v[134:137], v248 offset:1024
	ds_read_b128 v[138:141], v248 offset:2048
	ds_read_b128 v[142:145], v248 offset:3072
	ds_read_b128 v[146:149], v248 offset:16384
	ds_read_b128 v[150:153], v248 offset:17408
	ds_read_b128 v[154:157], v248 offset:18432
	ds_read_b128 v[158:161], v248 offset:19456
	s_add_i32 m0, s36, 0xc000
	ds_read_b128 v[162:165], v243
	ds_read_b128 v[166:169], v243 offset:1024
	ds_read_b128 v[170:173], v243 offset:2048
	ds_read_b128 v[174:177], v243 offset:3072
	ds_read_b128 v[178:181], v243 offset:4096
	ds_read_b128 v[182:185], v243 offset:5120
	ds_read_b128 v[186:189], v243 offset:6144
	ds_read_b128 v[190:193], v243 offset:7168
	global_load_lds_dwordx4 v202, s[4:5]
	s_add_i32 m0, s36, 0xe000
	s_nop 0
	global_load_lds_dwordx4 v204, s[4:5]
	s_waitcnt vmcnt(8)
	s_waitcnt lgkmcnt(0)
	s_barrier
	v_mfma_f32_16x16x32_bf16 v[126:129], v[130:133], v[162:165], v[126:129]
	v_mfma_f32_16x16x32_bf16 v[126:129], v[134:137], v[166:169], v[126:129]
	v_mfma_f32_16x16x32_bf16 v[122:125], v[142:145], v[166:169], v[122:125]
	v_mfma_f32_16x16x32_bf16 v[122:125], v[138:141], v[162:165], v[122:125]
	v_mfma_f32_16x16x32_bf16 v[118:121], v[146:149], v[162:165], v[118:121]
	v_mfma_f32_16x16x32_bf16 v[118:121], v[150:153], v[166:169], v[118:121]
	v_mfma_f32_16x16x32_bf16 v[114:117], v[158:161], v[166:169], v[114:117]
	v_mfma_f32_16x16x32_bf16 v[114:117], v[154:157], v[162:165], v[114:117]
	v_mfma_f32_16x16x32_bf16 v[98:101], v[154:157], v[170:173], v[98:101]
	v_mfma_f32_16x16x32_bf16 v[98:101], v[158:161], v[174:177], v[98:101]
	v_mfma_f32_16x16x32_bf16 v[106:109], v[142:145], v[174:177], v[106:109]
	v_mfma_f32_16x16x32_bf16 v[106:109], v[138:141], v[170:173], v[106:109]
	v_mfma_f32_16x16x32_bf16 v[110:113], v[130:133], v[170:173], v[110:113]
	v_mfma_f32_16x16x32_bf16 v[110:113], v[134:137], v[174:177], v[110:113]
	v_mfma_f32_16x16x32_bf16 v[102:105], v[150:153], v[174:177], v[102:105]
	v_mfma_f32_16x16x32_bf16 v[102:105], v[146:149], v[170:173], v[102:105]
	v_mfma_f32_16x16x32_bf16 v[86:89], v[146:149], v[178:181], v[86:89]
	v_mfma_f32_16x16x32_bf16 v[86:89], v[150:153], v[182:185], v[86:89]
	v_mfma_f32_16x16x32_bf16 v[94:97], v[134:137], v[182:185], v[94:97]
	v_mfma_f32_16x16x32_bf16 v[94:97], v[130:133], v[178:181], v[94:97]
	v_mfma_f32_16x16x32_bf16 v[90:93], v[138:141], v[178:181], v[90:93]
	v_mfma_f32_16x16x32_bf16 v[90:93], v[142:145], v[182:185], v[90:93]
	v_mfma_f32_16x16x32_bf16 v[82:85], v[158:161], v[182:185], v[82:85]
	v_mfma_f32_16x16x32_bf16 v[82:85], v[154:157], v[178:181], v[82:85]
	v_mfma_f32_16x16x32_bf16 v[66:69], v[154:157], v[186:189], v[66:69]
	v_mfma_f32_16x16x32_bf16 v[66:69], v[158:161], v[190:193], v[66:69]
	v_mfma_f32_16x16x32_bf16 v[74:77], v[142:145], v[190:193], v[74:77]
	v_mfma_f32_16x16x32_bf16 v[74:77], v[138:141], v[186:189], v[74:77]
	v_mfma_f32_16x16x32_bf16 v[78:81], v[130:133], v[186:189], v[78:81]
	v_mfma_f32_16x16x32_bf16 v[78:81], v[134:137], v[190:193], v[78:81]
	v_mfma_f32_16x16x32_bf16 v[70:73], v[150:153], v[190:193], v[70:73]
	v_mfma_f32_16x16x32_bf16 v[70:73], v[146:149], v[186:189], v[70:73]
	s_barrier
	s_add_i32 s4, s52, s1
	v_lshl_add_u64 v[194:195], s[30:31], 0, v[32:33]
	s_mov_b32 m0, s4
	ds_read_b128 v[162:165], v243 offset:16384
	ds_read_b128 v[166:169], v243 offset:17408
	ds_read_b128 v[170:173], v243 offset:18432
	ds_read_b128 v[174:177], v243 offset:19456
	ds_read_b128 v[178:181], v243 offset:20480
	ds_read_b128 v[182:185], v243 offset:21504
	ds_read_b128 v[186:189], v243 offset:22528
	ds_read_b128 v[190:193], v243 offset:23552
	global_load_lds_dwordx4 v[194:195], off
	s_add_i32 m0, s4, 0x2000
	s_add_u32 s4, s30, 0x160000
	v_lshl_add_u64 v[206:207], s[30:31], 0, v[200:201]
	s_addc_u32 s5, s31, 0
	s_add_i32 s52, s53, s1
	global_load_lds_dwordx4 v[206:207], off
	s_mov_b32 m0, s52
	v_lshl_add_u64 v[210:211], s[28:29], 0, v[198:199]
	global_load_lds_dwordx4 v32, s[4:5]
	s_add_i32 m0, s52, 0x2000
	s_nop 0
	global_load_lds_dwordx4 v200, s[4:5]
	v_lshl_add_u64 v[208:209], s[28:29], 0, v[196:197]
	s_mov_b32 m0, s36
	s_nop 0
	global_load_lds_dwordx4 v[208:209], off
	s_mov_b32 m0, s38
	s_nop 0
	global_load_lds_dwordx4 v[210:211], off
	s_waitcnt vmcnt(8)
	s_waitcnt lgkmcnt(0)
	s_barrier
	v_mfma_f32_16x16x32_bf16 v[62:65], v[130:133], v[162:165], v[62:65]
	v_mfma_f32_16x16x32_bf16 v[62:65], v[134:137], v[166:169], v[62:65]
	v_mfma_f32_16x16x32_bf16 v[58:61], v[142:145], v[166:169], v[58:61]
	v_mfma_f32_16x16x32_bf16 v[58:61], v[138:141], v[162:165], v[58:61]
	v_mfma_f32_16x16x32_bf16 v[54:57], v[146:149], v[162:165], v[54:57]
	v_mfma_f32_16x16x32_bf16 v[54:57], v[150:153], v[166:169], v[54:57]
	v_mfma_f32_16x16x32_bf16 v[50:53], v[158:161], v[166:169], v[50:53]
	v_mfma_f32_16x16x32_bf16 v[50:53], v[154:157], v[162:165], v[50:53]
	v_mfma_f32_16x16x32_bf16 v[34:37], v[154:157], v[170:173], v[34:37]
	v_mfma_f32_16x16x32_bf16 v[34:37], v[158:161], v[174:177], v[34:37]
	v_mfma_f32_16x16x32_bf16 v[42:45], v[142:145], v[174:177], v[42:45]
	v_mfma_f32_16x16x32_bf16 v[42:45], v[138:141], v[170:173], v[42:45]
	v_mfma_f32_16x16x32_bf16 v[46:49], v[130:133], v[170:173], v[46:49]
	v_mfma_f32_16x16x32_bf16 v[46:49], v[134:137], v[174:177], v[46:49]
	v_mfma_f32_16x16x32_bf16 v[38:41], v[150:153], v[174:177], v[38:41]
	v_mfma_f32_16x16x32_bf16 v[38:41], v[146:149], v[170:173], v[38:41]
	v_mfma_f32_16x16x32_bf16 v[20:23], v[146:149], v[178:181], v[20:23]
	v_mfma_f32_16x16x32_bf16 v[20:23], v[150:153], v[182:185], v[20:23]
	v_mfma_f32_16x16x32_bf16 v[28:31], v[134:137], v[182:185], v[28:31]
	v_mfma_f32_16x16x32_bf16 v[28:31], v[130:133], v[178:181], v[28:31]
	v_mfma_f32_16x16x32_bf16 v[24:27], v[138:141], v[178:181], v[24:27]
	v_mfma_f32_16x16x32_bf16 v[24:27], v[142:145], v[182:185], v[24:27]
	v_mfma_f32_16x16x32_bf16 v[16:19], v[158:161], v[182:185], v[16:19]
	v_mfma_f32_16x16x32_bf16 v[16:19], v[154:157], v[178:181], v[16:19]
	v_mfma_f32_16x16x32_bf16 v[0:3], v[154:157], v[186:189], v[0:3]
	v_mfma_f32_16x16x32_bf16 v[0:3], v[158:161], v[190:193], v[0:3]
	v_mfma_f32_16x16x32_bf16 v[8:11], v[142:145], v[190:193], v[8:11]
	v_mfma_f32_16x16x32_bf16 v[8:11], v[138:141], v[186:189], v[8:11]
	v_mfma_f32_16x16x32_bf16 v[12:15], v[130:133], v[186:189], v[12:15]
	v_mfma_f32_16x16x32_bf16 v[12:15], v[134:137], v[190:193], v[12:15]
	v_mfma_f32_16x16x32_bf16 v[4:7], v[150:153], v[190:193], v[4:7]
	v_mfma_f32_16x16x32_bf16 v[4:7], v[146:149], v[186:189], v[4:7]
	s_barrier
	s_add_i32 s52, 0, 0x18000
	s_add_i32 s53, 0, 0x1c000
	ds_read_b128 v[130:133], v248 offset:32768
	ds_read_b128 v[134:137], v248 offset:33792
	ds_read_b128 v[138:141], v248 offset:34816
	ds_read_b128 v[142:145], v248 offset:35840
	ds_read_b128 v[146:149], v248 offset:49152
	ds_read_b128 v[150:153], v248 offset:50176
	ds_read_b128 v[154:157], v248 offset:51200
	ds_read_b128 v[158:161], v248 offset:52224
	s_add_u32 s4, s28, 0x160000
	s_addc_u32 s5, s29, 0
	s_mov_b32 m0, s39
	ds_read_b128 v[162:165], v243 offset:32768
	ds_read_b128 v[166:169], v243 offset:33792
	ds_read_b128 v[170:173], v243 offset:34816
	ds_read_b128 v[174:177], v243 offset:35840
	ds_read_b128 v[178:181], v243 offset:36864
	ds_read_b128 v[182:185], v243 offset:37888
	ds_read_b128 v[186:189], v243 offset:38912
	ds_read_b128 v[190:193], v243 offset:39936
	global_load_lds_dwordx4 v196, s[4:5]
	s_mov_b32 m0, s42
	s_nop 0
	global_load_lds_dwordx4 v198, s[4:5]
	s_waitcnt vmcnt(8)
	s_waitcnt lgkmcnt(0)
	s_barrier
	v_mfma_f32_16x16x32_bf16 v[126:129], v[130:133], v[162:165], v[126:129]
	v_mfma_f32_16x16x32_bf16 v[126:129], v[134:137], v[166:169], v[126:129]
	v_mfma_f32_16x16x32_bf16 v[122:125], v[142:145], v[166:169], v[122:125]
	v_mfma_f32_16x16x32_bf16 v[122:125], v[138:141], v[162:165], v[122:125]
	v_mfma_f32_16x16x32_bf16 v[118:121], v[146:149], v[162:165], v[118:121]
	v_mfma_f32_16x16x32_bf16 v[118:121], v[150:153], v[166:169], v[118:121]
	v_mfma_f32_16x16x32_bf16 v[114:117], v[158:161], v[166:169], v[114:117]
	v_mfma_f32_16x16x32_bf16 v[114:117], v[154:157], v[162:165], v[114:117]
	v_mfma_f32_16x16x32_bf16 v[98:101], v[154:157], v[170:173], v[98:101]
	v_mfma_f32_16x16x32_bf16 v[98:101], v[158:161], v[174:177], v[98:101]
	v_mfma_f32_16x16x32_bf16 v[106:109], v[142:145], v[174:177], v[106:109]
	v_mfma_f32_16x16x32_bf16 v[106:109], v[138:141], v[170:173], v[106:109]
	v_mfma_f32_16x16x32_bf16 v[110:113], v[130:133], v[170:173], v[110:113]
	v_mfma_f32_16x16x32_bf16 v[110:113], v[134:137], v[174:177], v[110:113]
	v_mfma_f32_16x16x32_bf16 v[102:105], v[150:153], v[174:177], v[102:105]
	v_mfma_f32_16x16x32_bf16 v[102:105], v[146:149], v[170:173], v[102:105]
	v_mfma_f32_16x16x32_bf16 v[86:89], v[146:149], v[178:181], v[86:89]
	v_mfma_f32_16x16x32_bf16 v[86:89], v[150:153], v[182:185], v[86:89]
	v_mfma_f32_16x16x32_bf16 v[94:97], v[134:137], v[182:185], v[94:97]
	v_mfma_f32_16x16x32_bf16 v[94:97], v[130:133], v[178:181], v[94:97]
	v_mfma_f32_16x16x32_bf16 v[90:93], v[138:141], v[178:181], v[90:93]
	v_mfma_f32_16x16x32_bf16 v[90:93], v[142:145], v[182:185], v[90:93]
	v_mfma_f32_16x16x32_bf16 v[82:85], v[158:161], v[182:185], v[82:85]
	v_mfma_f32_16x16x32_bf16 v[82:85], v[154:157], v[178:181], v[82:85]
	v_mfma_f32_16x16x32_bf16 v[66:69], v[154:157], v[186:189], v[66:69]
	v_mfma_f32_16x16x32_bf16 v[66:69], v[158:161], v[190:193], v[66:69]
	v_mfma_f32_16x16x32_bf16 v[74:77], v[142:145], v[190:193], v[74:77]
	v_mfma_f32_16x16x32_bf16 v[74:77], v[138:141], v[186:189], v[74:77]
	v_mfma_f32_16x16x32_bf16 v[78:81], v[130:133], v[186:189], v[78:81]
	v_mfma_f32_16x16x32_bf16 v[78:81], v[134:137], v[190:193], v[78:81]
	v_mfma_f32_16x16x32_bf16 v[70:73], v[150:153], v[190:193], v[70:73]
	v_mfma_f32_16x16x32_bf16 v[70:73], v[146:149], v[186:189], v[70:73]
	s_barrier
	s_add_i32 s4, s52, s1
	v_lshl_add_u64 v[194:195], v[194:195], 0, s[34:35]
	s_mov_b32 m0, s4
	ds_read_b128 v[162:165], v243 offset:49152
	ds_read_b128 v[166:169], v243 offset:50176
	ds_read_b128 v[170:173], v243 offset:51200
	ds_read_b128 v[174:177], v243 offset:52224
	ds_read_b128 v[178:181], v243 offset:53248
	ds_read_b128 v[182:185], v243 offset:54272
	ds_read_b128 v[186:189], v243 offset:55296
	ds_read_b128 v[190:193], v243 offset:56320
	global_load_lds_dwordx4 v[194:195], off
	s_add_i32 m0, s4, 0x2000
	s_add_u32 s4, s30, 0x160080
	v_lshl_add_u64 v[194:195], v[206:207], 0, s[34:35]
	s_addc_u32 s5, s31, 0
	s_add_i32 s28, s53, s1
	global_load_lds_dwordx4 v[194:195], off
	s_mov_b32 m0, s28
	s_nop 0
	global_load_lds_dwordx4 v32, s[4:5]
	s_add_i32 m0, s28, 0x2000
	s_nop 0
	global_load_lds_dwordx4 v200, s[4:5]
	v_lshl_add_u64 v[194:195], v[208:209], 0, s[34:35]
	s_mov_b32 m0, s44
	s_nop 0
	global_load_lds_dwordx4 v[194:195], off
	v_lshl_add_u64 v[194:195], v[210:211], 0, s[34:35]
	s_mov_b32 m0, s45
	s_nop 0
	global_load_lds_dwordx4 v[194:195], off
	s_waitcnt vmcnt(8)
	s_waitcnt lgkmcnt(0)
	s_barrier
	v_mfma_f32_16x16x32_bf16 v[62:65], v[130:133], v[162:165], v[62:65]
	v_mfma_f32_16x16x32_bf16 v[62:65], v[134:137], v[166:169], v[62:65]
	v_mfma_f32_16x16x32_bf16 v[58:61], v[142:145], v[166:169], v[58:61]
	v_mfma_f32_16x16x32_bf16 v[58:61], v[138:141], v[162:165], v[58:61]
	v_mfma_f32_16x16x32_bf16 v[54:57], v[146:149], v[162:165], v[54:57]
	v_mfma_f32_16x16x32_bf16 v[54:57], v[150:153], v[166:169], v[54:57]
	v_mfma_f32_16x16x32_bf16 v[50:53], v[158:161], v[166:169], v[50:53]
	v_mfma_f32_16x16x32_bf16 v[50:53], v[154:157], v[162:165], v[50:53]
	v_mfma_f32_16x16x32_bf16 v[34:37], v[154:157], v[170:173], v[34:37]
	v_mfma_f32_16x16x32_bf16 v[34:37], v[158:161], v[174:177], v[34:37]
	v_mfma_f32_16x16x32_bf16 v[42:45], v[142:145], v[174:177], v[42:45]
	v_mfma_f32_16x16x32_bf16 v[42:45], v[138:141], v[170:173], v[42:45]
	v_mfma_f32_16x16x32_bf16 v[46:49], v[130:133], v[170:173], v[46:49]
	v_mfma_f32_16x16x32_bf16 v[46:49], v[134:137], v[174:177], v[46:49]
	v_mfma_f32_16x16x32_bf16 v[38:41], v[150:153], v[174:177], v[38:41]
	v_mfma_f32_16x16x32_bf16 v[38:41], v[146:149], v[170:173], v[38:41]
	v_mfma_f32_16x16x32_bf16 v[20:23], v[146:149], v[178:181], v[20:23]
	v_mfma_f32_16x16x32_bf16 v[20:23], v[150:153], v[182:185], v[20:23]
	v_mfma_f32_16x16x32_bf16 v[28:31], v[134:137], v[182:185], v[28:31]
	v_mfma_f32_16x16x32_bf16 v[28:31], v[130:133], v[178:181], v[28:31]
	v_mfma_f32_16x16x32_bf16 v[24:27], v[138:141], v[178:181], v[24:27]
	v_mfma_f32_16x16x32_bf16 v[24:27], v[142:145], v[182:185], v[24:27]
	v_mfma_f32_16x16x32_bf16 v[16:19], v[158:161], v[182:185], v[16:19]
	v_mfma_f32_16x16x32_bf16 v[16:19], v[154:157], v[178:181], v[16:19]
	v_mfma_f32_16x16x32_bf16 v[0:3], v[154:157], v[186:189], v[0:3]
	v_mfma_f32_16x16x32_bf16 v[0:3], v[158:161], v[190:193], v[0:3]
	v_mfma_f32_16x16x32_bf16 v[8:11], v[142:145], v[190:193], v[8:11]
	v_mfma_f32_16x16x32_bf16 v[8:11], v[138:141], v[186:189], v[8:11]
	v_mfma_f32_16x16x32_bf16 v[12:15], v[130:133], v[186:189], v[12:15]
	v_mfma_f32_16x16x32_bf16 v[12:15], v[134:137], v[190:193], v[12:15]
	v_mfma_f32_16x16x32_bf16 v[4:7], v[150:153], v[190:193], v[4:7]
	v_mfma_f32_16x16x32_bf16 v[4:7], v[146:149], v[186:189], v[4:7]
	s_barrier
	s_add_i32 s51, s51, 2
	s_add_u32 s33, s33, 0x100
	s_addc_u32 s50, s50, 0
	s_cmpk_gt_u32 s51, 0x55
	s_mov_b64 s[4:5], s[6:7]
	s_cbranch_scc0 .LBB0_755
	s_setprio 0
	s_and_b64 vcc, exec, s[18:19]
	s_cbranch_vccz .LBB0_758
	s_barrier

.LBB0_888:
	s_add_u32 s38, s16, s30
	s_addc_u32 s39, s17, s31
	s_add_u32 s38, s38, 0x100
	s_addc_u32 s39, s39, 0
	s_add_u32 s54, s50, s30
	s_addc_u32 s55, s51, s31
	s_add_i32 s56, 0, 0x10000
	s_cmpk_eq_i32 s30, 0xf00
	s_cselect_b32 s41, s29, s39
	s_cselect_b32 s40, s28, s38
	s_cselect_b32 s39, s21, s55
	s_cselect_b32 s38, s52, s54
	s_add_i32 s57, 0, 0x14000
	ds_read_b128 v[134:137], v224
	ds_read_b128 v[138:141], v224 offset:1024
	ds_read_b128 v[142:145], v224 offset:2048
	ds_read_b128 v[146:149], v224 offset:3072
	ds_read_b128 v[150:153], v224 offset:16384
	ds_read_b128 v[154:157], v224 offset:17408
	ds_read_b128 v[158:161], v224 offset:18432
	ds_read_b128 v[172:175], v224 offset:19456
	v_lshl_add_u64 v[212:213], v[130:131], 0, s[30:31]
	s_add_i32 m0, s24, 0xc000
	ds_read_b128 v[180:183], v179
	ds_read_b128 v[184:187], v179 offset:1024
	ds_read_b128 v[188:191], v179 offset:2048
	ds_read_b128 v[192:195], v179 offset:3072
	ds_read_b128 v[196:199], v179 offset:4096
	ds_read_b128 v[200:203], v179 offset:5120
	ds_read_b128 v[204:207], v179 offset:6144
	ds_read_b128 v[208:211], v179 offset:7168
	global_load_lds_dwordx4 v[212:213], off
	v_lshl_add_u64 v[212:213], v[132:133], 0, s[30:31]
	s_add_i32 m0, s24, 0xe000
	s_nop 0
	global_load_lds_dwordx4 v[212:213], off
	s_waitcnt vmcnt(8)
	s_waitcnt lgkmcnt(0)
	s_barrier
	v_mfma_f32_16x16x32_bf16 v[82:85], v[134:137], v[180:183], v[82:85]
	v_mfma_f32_16x16x32_bf16 v[82:85], v[138:141], v[184:187], v[82:85]
	v_mfma_f32_16x16x32_bf16 v[78:81], v[146:149], v[184:187], v[78:81]
	v_mfma_f32_16x16x32_bf16 v[78:81], v[142:145], v[180:183], v[78:81]
	v_mfma_f32_16x16x32_bf16 v[50:53], v[150:153], v[180:183], v[50:53]
	v_mfma_f32_16x16x32_bf16 v[50:53], v[154:157], v[184:187], v[50:53]
	v_mfma_f32_16x16x32_bf16 v[46:49], v[172:175], v[184:187], v[46:49]
	v_mfma_f32_16x16x32_bf16 v[46:49], v[158:161], v[180:183], v[46:49]
	v_mfma_f32_16x16x32_bf16 v[38:41], v[158:161], v[188:191], v[38:41]
	v_mfma_f32_16x16x32_bf16 v[38:41], v[172:175], v[192:195], v[38:41]
	v_mfma_f32_16x16x32_bf16 v[70:73], v[146:149], v[192:195], v[70:73]
	v_mfma_f32_16x16x32_bf16 v[70:73], v[142:145], v[188:191], v[70:73]
	v_mfma_f32_16x16x32_bf16 v[74:77], v[134:137], v[188:191], v[74:77]
	v_mfma_f32_16x16x32_bf16 v[74:77], v[138:141], v[192:195], v[74:77]
	v_mfma_f32_16x16x32_bf16 v[42:45], v[154:157], v[192:195], v[42:45]
	v_mfma_f32_16x16x32_bf16 v[42:45], v[150:153], v[188:191], v[42:45]
	v_mfma_f32_16x16x32_bf16 v[34:37], v[150:153], v[196:199], v[34:37]
	v_mfma_f32_16x16x32_bf16 v[34:37], v[154:157], v[200:203], v[34:37]
	v_mfma_f32_16x16x32_bf16 v[66:69], v[138:141], v[200:203], v[66:69]
	v_mfma_f32_16x16x32_bf16 v[66:69], v[134:137], v[196:199], v[66:69]
	v_mfma_f32_16x16x32_bf16 v[62:65], v[142:145], v[196:199], v[62:65]
	v_mfma_f32_16x16x32_bf16 v[62:65], v[146:149], v[200:203], v[62:65]
	v_mfma_f32_16x16x32_bf16 v[28:31], v[172:175], v[200:203], v[28:31]
	v_mfma_f32_16x16x32_bf16 v[28:31], v[158:161], v[196:199], v[28:31]
	v_mfma_f32_16x16x32_bf16 v[20:23], v[158:161], v[204:207], v[20:23]
	v_mfma_f32_16x16x32_bf16 v[20:23], v[172:175], v[208:211], v[20:23]
	v_mfma_f32_16x16x32_bf16 v[54:57], v[146:149], v[208:211], v[54:57]
	v_mfma_f32_16x16x32_bf16 v[54:57], v[142:145], v[204:207], v[54:57]
	v_mfma_f32_16x16x32_bf16 v[58:61], v[134:137], v[204:207], v[58:61]
	v_mfma_f32_16x16x32_bf16 v[58:61], v[138:141], v[208:211], v[58:61]
	v_mfma_f32_16x16x32_bf16 v[24:27], v[154:157], v[208:211], v[24:27]
	v_mfma_f32_16x16x32_bf16 v[24:27], v[150:153], v[204:207], v[24:27]
	s_barrier
	s_add_i32 s54, s56, s13
	v_lshl_add_u64 v[212:213], s[38:39], 0, v[32:33]
	s_mov_b32 m0, s54
	ds_read_b128 v[180:183], v179 offset:16384
	ds_read_b128 v[184:187], v179 offset:17408
	ds_read_b128 v[188:191], v179 offset:18432
	ds_read_b128 v[192:195], v179 offset:19456
	ds_read_b128 v[196:199], v179 offset:20480
	ds_read_b128 v[200:203], v179 offset:21504
	ds_read_b128 v[204:207], v179 offset:22528
	ds_read_b128 v[208:211], v179 offset:23552
	global_load_lds_dwordx4 v[212:213], off
	s_add_i32 m0, s54, 0x2000
	s_add_u32 s54, s38, 0x80000
	v_lshl_add_u64 v[214:215], s[38:39], 0, v[166:167]
	s_addc_u32 s55, s39, 0
	s_add_i32 s56, s57, s13
	global_load_lds_dwordx4 v[214:215], off
	s_mov_b32 m0, s56
	v_lshl_add_u64 v[220:221], s[40:41], 0, v[164:165]
	global_load_lds_dwordx4 v32, s[54:55]
	s_add_i32 m0, s56, 0x2000
	s_nop 0
	global_load_lds_dwordx4 v166, s[54:55]
	v_lshl_add_u64 v[216:217], s[40:41], 0, v[162:163]
	s_mov_b32 m0, s24
	s_nop 0
	global_load_lds_dwordx4 v[216:217], off
	s_mov_b32 m0, s25
	s_nop 0
	global_load_lds_dwordx4 v[220:221], off
	s_waitcnt vmcnt(8)
	s_waitcnt lgkmcnt(0)
	s_barrier
	v_mfma_f32_16x16x32_bf16 v[16:19], v[134:137], v[180:183], v[16:19]
	v_mfma_f32_16x16x32_bf16 v[16:19], v[138:141], v[184:187], v[16:19]
	v_mfma_f32_16x16x32_bf16 v[12:15], v[146:149], v[184:187], v[12:15]
	v_mfma_f32_16x16x32_bf16 v[12:15], v[142:145], v[180:183], v[12:15]
	v_mfma_f32_16x16x32_bf16 v[98:101], v[150:153], v[180:183], v[98:101]
	v_mfma_f32_16x16x32_bf16 v[98:101], v[154:157], v[184:187], v[98:101]
	v_mfma_f32_16x16x32_bf16 v[102:105], v[172:175], v[184:187], v[102:105]
	v_mfma_f32_16x16x32_bf16 v[102:105], v[158:161], v[180:183], v[102:105]
	v_mfma_f32_16x16x32_bf16 v[110:113], v[158:161], v[188:191], v[110:113]
	v_mfma_f32_16x16x32_bf16 v[110:113], v[172:175], v[192:195], v[110:113]
	v_mfma_f32_16x16x32_bf16 v[4:7], v[146:149], v[192:195], v[4:7]
	v_mfma_f32_16x16x32_bf16 v[4:7], v[142:145], v[188:191], v[4:7]
	v_mfma_f32_16x16x32_bf16 v[8:11], v[134:137], v[188:191], v[8:11]
	v_mfma_f32_16x16x32_bf16 v[8:11], v[138:141], v[192:195], v[8:11]
	v_mfma_f32_16x16x32_bf16 v[106:109], v[154:157], v[192:195], v[106:109]
	v_mfma_f32_16x16x32_bf16 v[106:109], v[150:153], v[188:191], v[106:109]
	v_mfma_f32_16x16x32_bf16 v[114:117], v[150:153], v[196:199], v[114:117]
	v_mfma_f32_16x16x32_bf16 v[114:117], v[154:157], v[200:203], v[114:117]
	v_mfma_f32_16x16x32_bf16 v[0:3], v[138:141], v[200:203], v[0:3]
	v_mfma_f32_16x16x32_bf16 v[0:3], v[134:137], v[196:199], v[0:3]
	v_mfma_f32_16x16x32_bf16 v[86:89], v[142:145], v[196:199], v[86:89]
	v_mfma_f32_16x16x32_bf16 v[86:89], v[146:149], v[200:203], v[86:89]
	v_mfma_f32_16x16x32_bf16 v[118:121], v[172:175], v[200:203], v[118:121]
	v_mfma_f32_16x16x32_bf16 v[118:121], v[158:161], v[196:199], v[118:121]
	v_mfma_f32_16x16x32_bf16 v[126:129], v[158:161], v[204:207], v[126:129]
	v_mfma_f32_16x16x32_bf16 v[126:129], v[172:175], v[208:211], v[126:129]
	v_mfma_f32_16x16x32_bf16 v[94:97], v[146:149], v[208:211], v[94:97]
	v_mfma_f32_16x16x32_bf16 v[94:97], v[142:145], v[204:207], v[94:97]
	v_mfma_f32_16x16x32_bf16 v[90:93], v[134:137], v[204:207], v[90:93]
	v_mfma_f32_16x16x32_bf16 v[90:93], v[138:141], v[208:211], v[90:93]
	v_mfma_f32_16x16x32_bf16 v[122:125], v[154:157], v[208:211], v[122:125]
	v_mfma_f32_16x16x32_bf16 v[122:125], v[150:153], v[204:207], v[122:125]
	s_barrier
	s_add_i32 s54, 0, 0x18000
	s_add_i32 s55, 0, 0x1c000
	ds_read_b128 v[134:137], v224 offset:32768
	ds_read_b128 v[138:141], v224 offset:33792
	ds_read_b128 v[142:145], v224 offset:34816
	ds_read_b128 v[146:149], v224 offset:35840
	ds_read_b128 v[150:153], v224 offset:49152
	ds_read_b128 v[154:157], v224 offset:50176
	ds_read_b128 v[158:161], v224 offset:51200
	ds_read_b128 v[172:175], v224 offset:52224
	s_add_u32 s40, s40, 0x80000
	s_addc_u32 s41, s41, 0
	s_mov_b32 m0, s33
	ds_read_b128 v[180:183], v179 offset:32768
	ds_read_b128 v[184:187], v179 offset:33792
	ds_read_b128 v[188:191], v179 offset:34816
	ds_read_b128 v[192:195], v179 offset:35840
	ds_read_b128 v[196:199], v179 offset:36864
	ds_read_b128 v[200:203], v179 offset:37888
	ds_read_b128 v[204:207], v179 offset:38912
	ds_read_b128 v[208:211], v179 offset:39936
	global_load_lds_dwordx4 v162, s[40:41]
	s_mov_b32 m0, s36
	s_nop 0
	global_load_lds_dwordx4 v164, s[40:41]
	s_waitcnt vmcnt(8)
	s_waitcnt lgkmcnt(0)
	s_barrier
	v_mfma_f32_16x16x32_bf16 v[82:85], v[134:137], v[180:183], v[82:85]
	v_mfma_f32_16x16x32_bf16 v[82:85], v[138:141], v[184:187], v[82:85]
	v_mfma_f32_16x16x32_bf16 v[78:81], v[146:149], v[184:187], v[78:81]
	v_mfma_f32_16x16x32_bf16 v[78:81], v[142:145], v[180:183], v[78:81]
	v_mfma_f32_16x16x32_bf16 v[50:53], v[150:153], v[180:183], v[50:53]
	v_mfma_f32_16x16x32_bf16 v[50:53], v[154:157], v[184:187], v[50:53]
	v_mfma_f32_16x16x32_bf16 v[46:49], v[172:175], v[184:187], v[46:49]
	v_mfma_f32_16x16x32_bf16 v[46:49], v[158:161], v[180:183], v[46:49]
	v_mfma_f32_16x16x32_bf16 v[38:41], v[158:161], v[188:191], v[38:41]
	v_mfma_f32_16x16x32_bf16 v[38:41], v[172:175], v[192:195], v[38:41]
	v_mfma_f32_16x16x32_bf16 v[70:73], v[146:149], v[192:195], v[70:73]
	v_mfma_f32_16x16x32_bf16 v[70:73], v[142:145], v[188:191], v[70:73]
	v_mfma_f32_16x16x32_bf16 v[74:77], v[134:137], v[188:191], v[74:77]
	v_mfma_f32_16x16x32_bf16 v[74:77], v[138:141], v[192:195], v[74:77]
	v_mfma_f32_16x16x32_bf16 v[42:45], v[154:157], v[192:195], v[42:45]
	v_mfma_f32_16x16x32_bf16 v[42:45], v[150:153], v[188:191], v[42:45]
	v_mfma_f32_16x16x32_bf16 v[34:37], v[150:153], v[196:199], v[34:37]
	v_mfma_f32_16x16x32_bf16 v[34:37], v[154:157], v[200:203], v[34:37]
	v_mfma_f32_16x16x32_bf16 v[66:69], v[138:141], v[200:203], v[66:69]
	v_mfma_f32_16x16x32_bf16 v[66:69], v[134:137], v[196:199], v[66:69]
	v_mfma_f32_16x16x32_bf16 v[62:65], v[142:145], v[196:199], v[62:65]
	v_mfma_f32_16x16x32_bf16 v[62:65], v[146:149], v[200:203], v[62:65]
	v_mfma_f32_16x16x32_bf16 v[28:31], v[172:175], v[200:203], v[28:31]
	v_mfma_f32_16x16x32_bf16 v[28:31], v[158:161], v[196:199], v[28:31]
	v_mfma_f32_16x16x32_bf16 v[20:23], v[158:161], v[204:207], v[20:23]
	v_mfma_f32_16x16x32_bf16 v[20:23], v[172:175], v[208:211], v[20:23]
	v_mfma_f32_16x16x32_bf16 v[54:57], v[146:149], v[208:211], v[54:57]
	v_mfma_f32_16x16x32_bf16 v[54:57], v[142:145], v[204:207], v[54:57]
	v_mfma_f32_16x16x32_bf16 v[58:61], v[134:137], v[204:207], v[58:61]
	v_mfma_f32_16x16x32_bf16 v[58:61], v[138:141], v[208:211], v[58:61]
	v_mfma_f32_16x16x32_bf16 v[24:27], v[154:157], v[208:211], v[24:27]
	v_mfma_f32_16x16x32_bf16 v[24:27], v[150:153], v[204:207], v[24:27]
	s_barrier
	s_add_i32 s40, s54, s13
	v_lshl_add_u64 v[212:213], v[212:213], 0, s[34:35]
	s_mov_b32 m0, s40
	ds_read_b128 v[180:183], v179 offset:49152
	ds_read_b128 v[184:187], v179 offset:50176
	ds_read_b128 v[188:191], v179 offset:51200
	ds_read_b128 v[192:195], v179 offset:52224
	ds_read_b128 v[196:199], v179 offset:53248
	ds_read_b128 v[200:203], v179 offset:54272
	ds_read_b128 v[204:207], v179 offset:55296
	ds_read_b128 v[208:211], v179 offset:56320
	global_load_lds_dwordx4 v[212:213], off
	s_add_i32 m0, s40, 0x2000
	s_add_u32 s38, s38, 0x80080
	v_lshl_add_u64 v[212:213], v[214:215], 0, s[34:35]
	s_addc_u32 s39, s39, 0
	s_add_i32 s40, s55, s13
	global_load_lds_dwordx4 v[212:213], off
	s_mov_b32 m0, s40
	s_nop 0
	global_load_lds_dwordx4 v32, s[38:39]
	s_add_i32 m0, s40, 0x2000
	s_nop 0
	global_load_lds_dwordx4 v166, s[38:39]
	v_lshl_add_u64 v[212:213], v[216:217], 0, s[34:35]
	s_mov_b32 m0, s43
	s_nop 0
	global_load_lds_dwordx4 v[212:213], off
	v_lshl_add_u64 v[212:213], v[220:221], 0, s[34:35]
	s_mov_b32 m0, s44
	s_nop 0
	global_load_lds_dwordx4 v[212:213], off
	s_waitcnt vmcnt(8)
	s_waitcnt lgkmcnt(0)
	s_barrier
	v_mfma_f32_16x16x32_bf16 v[16:19], v[134:137], v[180:183], v[16:19]
	v_mfma_f32_16x16x32_bf16 v[16:19], v[138:141], v[184:187], v[16:19]
	v_mfma_f32_16x16x32_bf16 v[12:15], v[146:149], v[184:187], v[12:15]
	v_mfma_f32_16x16x32_bf16 v[12:15], v[142:145], v[180:183], v[12:15]
	v_mfma_f32_16x16x32_bf16 v[98:101], v[150:153], v[180:183], v[98:101]
	v_mfma_f32_16x16x32_bf16 v[98:101], v[154:157], v[184:187], v[98:101]
	v_mfma_f32_16x16x32_bf16 v[102:105], v[172:175], v[184:187], v[102:105]
	v_mfma_f32_16x16x32_bf16 v[102:105], v[158:161], v[180:183], v[102:105]
	v_mfma_f32_16x16x32_bf16 v[110:113], v[158:161], v[188:191], v[110:113]
	v_mfma_f32_16x16x32_bf16 v[110:113], v[172:175], v[192:195], v[110:113]
	v_mfma_f32_16x16x32_bf16 v[4:7], v[146:149], v[192:195], v[4:7]
	v_mfma_f32_16x16x32_bf16 v[4:7], v[142:145], v[188:191], v[4:7]
	v_mfma_f32_16x16x32_bf16 v[8:11], v[134:137], v[188:191], v[8:11]
	v_mfma_f32_16x16x32_bf16 v[8:11], v[138:141], v[192:195], v[8:11]
	v_mfma_f32_16x16x32_bf16 v[106:109], v[154:157], v[192:195], v[106:109]
	v_mfma_f32_16x16x32_bf16 v[106:109], v[150:153], v[188:191], v[106:109]
	v_mfma_f32_16x16x32_bf16 v[114:117], v[150:153], v[196:199], v[114:117]
	v_mfma_f32_16x16x32_bf16 v[114:117], v[154:157], v[200:203], v[114:117]
	v_mfma_f32_16x16x32_bf16 v[0:3], v[138:141], v[200:203], v[0:3]
	v_mfma_f32_16x16x32_bf16 v[0:3], v[134:137], v[196:199], v[0:3]
	v_mfma_f32_16x16x32_bf16 v[86:89], v[142:145], v[196:199], v[86:89]
	v_mfma_f32_16x16x32_bf16 v[86:89], v[146:149], v[200:203], v[86:89]
	v_mfma_f32_16x16x32_bf16 v[118:121], v[172:175], v[200:203], v[118:121]
	v_mfma_f32_16x16x32_bf16 v[118:121], v[158:161], v[196:199], v[118:121]
	v_mfma_f32_16x16x32_bf16 v[126:129], v[158:161], v[204:207], v[126:129]
	v_mfma_f32_16x16x32_bf16 v[126:129], v[172:175], v[208:211], v[126:129]
	v_mfma_f32_16x16x32_bf16 v[94:97], v[146:149], v[208:211], v[94:97]
	v_mfma_f32_16x16x32_bf16 v[94:97], v[142:145], v[204:207], v[94:97]
	v_mfma_f32_16x16x32_bf16 v[90:93], v[134:137], v[204:207], v[90:93]
	v_mfma_f32_16x16x32_bf16 v[90:93], v[138:141], v[208:211], v[90:93]
	v_mfma_f32_16x16x32_bf16 v[122:125], v[154:157], v[208:211], v[122:125]
	v_mfma_f32_16x16x32_bf16 v[122:125], v[150:153], v[204:207], v[122:125]
	s_barrier
	s_add_i32 s53, s53, 2
	s_add_u32 s30, s30, 0x100
	s_addc_u32 s31, s31, 0
	s_cmp_gt_u32 s53, 29
	s_cbranch_scc0 .LBB0_888
	s_setprio 0
	s_and_b64 vcc, exec, s[18:19]
	s_cbranch_vccz .LBB0_891
	s_barrier
